# weight conversion in the gate/up tails: non-temporal hint on the read-once f32 weight loads
# speedup vs baseline: 1.0050x; 1.0039x over previous
.LBB0_865:
	s_cmpk_gt_i32 s18, 0x2ff
	s_mov_b64 s[10:11], -1
	s_cbranch_scc0 .LBB0_875
	s_cmpk_gt_u32 s18, 0x3ff
	s_cbranch_scc0 .LBB0_872
	s_cmpk_gt_u32 s18, 0x43f
	v_lshlrev_b32_e32 v0, 2, v68
	s_cbranch_scc0 .LBB0_869
	s_add_i32 s0, s18, 0xfffffbc0
	s_lshr_b32 s0, s0, 6
	v_readlane_b32 s36, v253, 1
	s_lshl_b64 s[10:11], s[0:1], 20
	v_readlane_b32 s42, v253, 7
	v_readlane_b32 s43, v253, 8
	s_add_u32 s12, s42, s10
	s_addc_u32 s13, s43, s11
	s_and_b32 s14, s7, 64
	s_lshl_b32 s0, s0, 7
	s_and_b32 s11, s9, 0x7c0
	s_or_b32 s10, s0, s14
	s_lshl_b32 s0, s14, 2
	s_add_u32 s12, s12, s0
	v_or_b32_e32 v4, s11, v66
	s_addc_u32 s13, s13, 0
	v_lshl_add_u64 v[2:3], s[12:13], 0, v[0:1]
	v_lshlrev_b32_e32 v4, 9, v4
	v_mov_b32_e32 v5, v1
	v_lshl_add_u64 v[58:59], v[2:3], 0, v[4:5]
	global_load_dwordx4 v[2:5], v[58:59], off nt
	global_load_dwordx4 v[6:9], v[58:59], off offset:2048 nt
	s_movk_i32 s0, 0x1000
	v_add_co_u32_e32 v14, vcc, s0, v58
	s_movk_i32 s0, 0x2000
	s_nop 0
	v_addc_co_u32_e32 v15, vcc, 0, v59, vcc
	v_add_co_u32_e32 v22, vcc, s0, v58
	s_movk_i32 s0, 0x3000
	s_nop 0
	v_addc_co_u32_e32 v23, vcc, 0, v59, vcc
	global_load_dwordx4 v[10:13], v[22:23], off offset:-4096
	s_nop 0
	global_load_dwordx4 v[14:17], v[14:15], off offset:2048 nt
	s_nop 0
	global_load_dwordx4 v[18:21], v[22:23], off nt
	s_nop 0
	global_load_dwordx4 v[22:25], v[22:23], off offset:2048 nt
	v_add_co_u32_e32 v30, vcc, s0, v58
	s_movk_i32 s0, 0x4000
	s_nop 0
	v_addc_co_u32_e32 v31, vcc, 0, v59, vcc
	v_add_co_u32_e32 v38, vcc, s0, v58
	s_movk_i32 s0, 0x5000
	s_nop 0
	v_addc_co_u32_e32 v39, vcc, 0, v59, vcc
	global_load_dwordx4 v[26:29], v[38:39], off offset:-4096
	s_nop 0
	global_load_dwordx4 v[30:33], v[30:31], off offset:2048 nt
	s_nop 0
	global_load_dwordx4 v[34:37], v[38:39], off nt
	s_nop 0
	global_load_dwordx4 v[38:41], v[38:39], off offset:2048 nt
	v_add_co_u32_e32 v46, vcc, s0, v58
	s_movk_i32 s0, 0x6000
	s_nop 0
	v_addc_co_u32_e32 v47, vcc, 0, v59, vcc
	v_add_co_u32_e32 v54, vcc, s0, v58
	s_movk_i32 s0, 0x7000
	s_nop 0
	v_addc_co_u32_e32 v55, vcc, 0, v59, vcc
	global_load_dwordx4 v[42:45], v[54:55], off offset:-4096
	s_nop 0
	global_load_dwordx4 v[46:49], v[46:47], off offset:2048 nt
	s_nop 0
	global_load_dwordx4 v[50:53], v[54:55], off nt
	s_nop 0
	global_load_dwordx4 v[54:57], v[54:55], off offset:2048 nt
	v_add_co_u32_e32 v62, vcc, s0, v58
	s_lshl_b32 s0, s11, 1
	s_nop 0
	v_addc_co_u32_e32 v63, vcc, 0, v59, vcc
	global_load_dwordx4 v[58:61], v[62:63], off nt
	s_nop 0
	global_load_dwordx4 v[62:65], v[62:63], off offset:2048 nt
	v_readlane_b32 s37, v253, 2
	v_readlane_b32 s38, v253, 3
	v_readlane_b32 s39, v253, 4
	v_readlane_b32 s40, v253, 5
	v_readlane_b32 s41, v253, 6
	v_readlane_b32 s44, v253, 9
	v_readlane_b32 s45, v253, 10
	v_readlane_b32 s46, v253, 11
	v_readlane_b32 s47, v253, 12
	v_readlane_b32 s48, v253, 13
	v_readlane_b32 s49, v253, 14
	v_readlane_b32 s50, v253, 15
	v_readlane_b32 s51, v253, 16
	s_waitcnt vmcnt(0)
	ds_write2_b32 v69, v2, v3 offset1:1
	ds_write2_b32 v69, v4, v5 offset0:2 offset1:3
	v_add_u32_e32 v2, 0x410, v69
	ds_write2_b32 v2, v6, v7 offset1:1
	v_add_u32_e32 v2, 0x418, v69
	ds_write2_b32 v2, v8, v9 offset1:1
	v_add_u32_e32 v2, 0x820, v69
	ds_write2_b32 v2, v10, v11 offset1:1
	v_add_u32_e32 v2, 0x828, v69
	ds_write2_b32 v2, v12, v13 offset1:1
	v_add_u32_e32 v2, 0xc30, v69
	ds_write2_b32 v2, v14, v15 offset1:1
	v_add_u32_e32 v2, 0xc38, v69
	ds_write2_b32 v2, v16, v17 offset1:1
	v_add_u32_e32 v2, 0x1040, v69
	ds_write2_b32 v2, v18, v19 offset1:1
	v_add_u32_e32 v2, 0x1048, v69
	ds_write2_b32 v2, v20, v21 offset1:1
	v_add_u32_e32 v2, 0x1450, v69
	ds_write2_b32 v2, v22, v23 offset1:1
	v_add_u32_e32 v2, 0x1458, v69
	ds_write2_b32 v2, v24, v25 offset1:1
	v_add_u32_e32 v2, 0x1860, v69
	ds_write2_b32 v2, v26, v27 offset1:1
	v_add_u32_e32 v2, 0x1868, v69
	ds_write2_b32 v2, v28, v29 offset1:1
	v_add_u32_e32 v2, 0x1c70, v69
	ds_write2_b32 v2, v30, v31 offset1:1
	v_add_u32_e32 v2, 0x1c78, v69
	ds_write2_b32 v2, v32, v33 offset1:1
	v_add_u32_e32 v2, 0x2080, v69
	ds_write2_b32 v2, v34, v35 offset1:1
	v_add_u32_e32 v2, 0x2088, v69
	ds_write2_b32 v2, v36, v37 offset1:1
	v_add_u32_e32 v2, 0x2490, v69
	ds_write2_b32 v2, v38, v39 offset1:1
	v_add_u32_e32 v2, 0x2498, v69
	ds_write2_b32 v2, v40, v41 offset1:1
	v_add_u32_e32 v2, 0x28a0, v69
	ds_write2_b32 v2, v42, v43 offset1:1
	v_add_u32_e32 v2, 0x28a8, v69
	ds_write2_b32 v2, v44, v45 offset1:1
	v_add_u32_e32 v2, 0x2cb0, v69
	ds_write2_b32 v2, v46, v47 offset1:1
	v_add_u32_e32 v2, 0x2cb8, v69
	ds_write2_b32 v2, v48, v49 offset1:1
	v_add_u32_e32 v2, 0x30c0, v69
	ds_write2_b32 v2, v50, v51 offset1:1
	v_add_u32_e32 v2, 0x30c8, v69
	ds_write2_b32 v2, v52, v53 offset1:1
	v_add_u32_e32 v2, 0x34d0, v69
	ds_write2_b32 v2, v54, v55 offset1:1
	v_add_u32_e32 v2, 0x34d8, v69
	ds_write2_b32 v2, v56, v57 offset1:1
	v_add_u32_e32 v2, 0x38e0, v69
	ds_write2_b32 v2, v58, v59 offset1:1
	v_add_u32_e32 v2, 0x38e8, v69
	ds_write2_b32 v2, v60, v61 offset1:1
	v_add_u32_e32 v2, 0x3cf0, v69
	ds_write2_b32 v2, v62, v63 offset1:1
	v_add_u32_e32 v2, 0x3cf8, v69
	ds_write2_b32 v2, v64, v65 offset1:1
	s_waitcnt lgkmcnt(0)
	v_add_u32_e32 v26, 0x400, v87
	ds_read2_b32 v[8:9], v87 offset0:65 offset1:73
	ds_read2_b32 v[10:11], v87 offset1:8
	ds_read2_b32 v[12:13], v87 offset0:130 offset1:138
	ds_read2_b32 v[14:15], v87 offset0:195 offset1:203
	ds_read2_b32 v[16:17], v26 offset0:4 offset1:12
	ds_read2_b32 v[18:19], v26 offset0:69 offset1:77
	ds_read2_b32 v[20:21], v26 offset0:134 offset1:142
	ds_read2_b32 v[22:23], v26 offset0:199 offset1:207
	v_or_b32_e32 v24, s10, v86
	v_mov_b32_e32 v25, v1
	v_lshl_add_u64 v[2:3], v[70:71], 0, s[0:1]
	v_lshlrev_b64 v[24:25], 12, v[24:25]
	s_waitcnt lgkmcnt(6)
	v_cvt_pk_bf16_f32 v4, v10, v8
	s_waitcnt lgkmcnt(4)
	v_cvt_pk_bf16_f32 v5, v12, v14
	s_waitcnt lgkmcnt(2)
	v_cvt_pk_bf16_f32 v6, v16, v18
	s_waitcnt lgkmcnt(0)
	v_cvt_pk_bf16_f32 v7, v20, v22
	v_lshl_add_u64 v[24:25], v[2:3], 0, v[24:25]
	global_store_dwordx4 v[24:25], v[4:7], off
	v_or_b32_e32 v8, s10, v88
	v_or_b32_e32 v24, s10, v89
	v_cvt_pk_bf16_f32 v4, v11, v9
	v_mov_b32_e32 v9, v1
	v_lshlrev_b64 v[8:9], 12, v[8:9]
	v_cvt_pk_bf16_f32 v5, v13, v15
	v_cvt_pk_bf16_f32 v6, v17, v19
	v_cvt_pk_bf16_f32 v7, v21, v23
	v_lshl_add_u64 v[8:9], v[2:3], 0, v[8:9]
	global_store_dwordx4 v[8:9], v[4:7], off
	ds_read2_b32 v[8:9], v87 offset0:81 offset1:89
	ds_read2_b32 v[10:11], v87 offset0:16 offset1:24
	ds_read2_b32 v[12:13], v87 offset0:146 offset1:154
	ds_read2_b32 v[14:15], v87 offset0:211 offset1:219
	ds_read2_b32 v[16:17], v26 offset0:20 offset1:28
	ds_read2_b32 v[18:19], v26 offset0:85 offset1:93
	ds_read2_b32 v[20:21], v26 offset0:150 offset1:158
	ds_read2_b32 v[22:23], v26 offset0:215 offset1:223
	v_mov_b32_e32 v25, v1
	v_lshlrev_b64 v[24:25], 12, v[24:25]
	s_waitcnt lgkmcnt(6)
	v_cvt_pk_bf16_f32 v4, v10, v8
	s_waitcnt lgkmcnt(4)
	v_cvt_pk_bf16_f32 v5, v12, v14
	s_waitcnt lgkmcnt(2)
	v_cvt_pk_bf16_f32 v6, v16, v18
	s_waitcnt lgkmcnt(0)
	v_cvt_pk_bf16_f32 v7, v20, v22
	v_lshl_add_u64 v[24:25], v[2:3], 0, v[24:25]
	global_store_dwordx4 v[24:25], v[4:7], off
	v_or_b32_e32 v8, s10, v90
	v_or_b32_e32 v24, s10, v91
	v_cvt_pk_bf16_f32 v4, v11, v9
	v_mov_b32_e32 v9, v1
	v_lshlrev_b64 v[8:9], 12, v[8:9]
	v_cvt_pk_bf16_f32 v5, v13, v15
	v_cvt_pk_bf16_f32 v6, v17, v19
	v_cvt_pk_bf16_f32 v7, v21, v23
	v_lshl_add_u64 v[8:9], v[2:3], 0, v[8:9]
	global_store_dwordx4 v[8:9], v[4:7], off
	ds_read2_b32 v[8:9], v87 offset0:32 offset1:40
	ds_read2_b32 v[10:11], v87 offset0:97 offset1:105
	ds_read2_b32 v[12:13], v87 offset0:162 offset1:170
	ds_read2_b32 v[14:15], v87 offset0:227 offset1:235
	ds_read2_b32 v[16:17], v26 offset0:36 offset1:44
	ds_read2_b32 v[18:19], v26 offset0:101 offset1:109
	ds_read2_b32 v[20:21], v26 offset0:166 offset1:174
	ds_read2_b32 v[22:23], v26 offset0:231 offset1:239
	v_mov_b32_e32 v25, v1
	v_lshlrev_b64 v[24:25], 12, v[24:25]
	s_waitcnt lgkmcnt(6)
	v_cvt_pk_bf16_f32 v4, v8, v10
	s_waitcnt lgkmcnt(4)
	v_cvt_pk_bf16_f32 v5, v12, v14
	s_waitcnt lgkmcnt(2)
	v_cvt_pk_bf16_f32 v6, v16, v18
	s_waitcnt lgkmcnt(0)
	v_cvt_pk_bf16_f32 v7, v20, v22
	v_lshl_add_u64 v[24:25], v[2:3], 0, v[24:25]
	global_store_dwordx4 v[24:25], v[4:7], off
	v_or_b32_e32 v8, s10, v92
	v_or_b32_e32 v24, s10, v93
	v_cvt_pk_bf16_f32 v4, v9, v11
	v_mov_b32_e32 v9, v1
	v_lshlrev_b64 v[8:9], 12, v[8:9]
	v_cvt_pk_bf16_f32 v5, v13, v15
	v_cvt_pk_bf16_f32 v6, v17, v19
	v_cvt_pk_bf16_f32 v7, v21, v23
	v_lshl_add_u64 v[8:9], v[2:3], 0, v[8:9]
	global_store_dwordx4 v[8:9], v[4:7], off
	ds_read2_b32 v[8:9], v87 offset0:48 offset1:56
	ds_read2_b32 v[10:11], v87 offset0:113 offset1:121
	ds_read2_b32 v[12:13], v87 offset0:178 offset1:186
	ds_read2_b32 v[14:15], v87 offset0:243 offset1:251
	ds_read2_b32 v[16:17], v26 offset0:52 offset1:60
	ds_read2_b32 v[18:19], v26 offset0:117 offset1:125
	ds_read2_b32 v[20:21], v26 offset0:182 offset1:190
	ds_read2_b32 v[22:23], v26 offset0:247 offset1:255
	v_mov_b32_e32 v25, v1
	v_lshlrev_b64 v[24:25], 12, v[24:25]
	s_waitcnt lgkmcnt(6)
	v_cvt_pk_bf16_f32 v4, v8, v10
	s_waitcnt lgkmcnt(4)
	v_cvt_pk_bf16_f32 v5, v12, v14
	s_waitcnt lgkmcnt(2)
	v_cvt_pk_bf16_f32 v6, v16, v18
	s_waitcnt lgkmcnt(0)
	v_cvt_pk_bf16_f32 v7, v20, v22
	v_lshl_add_u64 v[24:25], v[2:3], 0, v[24:25]
	global_store_dwordx4 v[24:25], v[4:7], off
	v_or_b32_e32 v8, s10, v94
	s_mov_b64 s[10:11], 0
	v_cvt_pk_bf16_f32 v4, v9, v11
	v_mov_b32_e32 v9, v1
	v_lshlrev_b64 v[8:9], 12, v[8:9]
	v_cvt_pk_bf16_f32 v5, v13, v15
	v_cvt_pk_bf16_f32 v6, v17, v19
	v_cvt_pk_bf16_f32 v7, v21, v23
	v_lshl_add_u64 v[2:3], v[2:3], 0, v[8:9]
	global_store_dwordx4 v[2:3], v[4:7], off
	s_waitcnt lgkmcnt(0)
.LBB0_869:
	s_andn2_b64 vcc, exec, s[10:11]
	s_cbranch_vccnz .LBB0_871
	s_add_i32 s0, s18, 0xfffffc00
	s_lshr_b32 s0, s0, 4
	v_readlane_b32 s36, v253, 1
	s_lshl_b64 s[10:11], s[0:1], 18
	v_readlane_b32 s50, v253, 15
	v_readlane_b32 s51, v253, 16
	s_add_u32 s12, s50, s10
	s_addc_u32 s13, s51, s11
	s_and_b32 s14, s7, 0xc0
	s_lshl_b32 s0, s0, 8
	s_and_b32 s11, s16, 0xc0
	s_or_b32 s10, s0, s14
	s_lshl_b32 s0, s14, 2
	s_add_u32 s12, s12, s0
	v_or_b32_e32 v4, s11, v66
	s_addc_u32 s13, s13, 0
	v_lshl_add_u64 v[2:3], s[12:13], 0, v[0:1]
	v_lshlrev_b32_e32 v0, 10, v4
	v_lshl_add_u64 v[62:63], v[2:3], 0, v[0:1]
	s_movk_i32 s0, 0x2000
	v_add_co_u32_e32 v10, vcc, s0, v62
	global_load_dwordx4 v[2:5], v[62:63], off nt
	s_nop 0
	v_addc_co_u32_e32 v11, vcc, 0, v63, vcc
	global_load_dwordx4 v[6:9], v[10:11], off offset:-4096
	s_nop 0
	global_load_dwordx4 v[10:13], v[10:11], off nt
	s_movk_i32 s0, 0x4000
	v_add_co_u32_e32 v18, vcc, s0, v62
	s_movk_i32 s0, 0x6000
	s_nop 0
	v_addc_co_u32_e32 v19, vcc, 0, v63, vcc
	global_load_dwordx4 v[14:17], v[18:19], off offset:-4096
	s_nop 0
	global_load_dwordx4 v[18:21], v[18:19], off nt
	v_add_co_u32_e32 v26, vcc, s0, v62
	s_mov_b32 s0, 0x8000
	s_nop 0
	v_addc_co_u32_e32 v27, vcc, 0, v63, vcc
	global_load_dwordx4 v[22:25], v[26:27], off offset:-4096
	s_nop 0
	global_load_dwordx4 v[26:29], v[26:27], off nt
	v_add_co_u32_e32 v34, vcc, s0, v62
	s_mov_b32 s0, 0xa000
	s_nop 0
	v_addc_co_u32_e32 v35, vcc, 0, v63, vcc
	global_load_dwordx4 v[30:33], v[34:35], off offset:-4096
	s_nop 0
	global_load_dwordx4 v[34:37], v[34:35], off nt
	v_add_co_u32_e32 v42, vcc, s0, v62
	s_mov_b32 s0, 0xc000
	s_nop 0
	v_addc_co_u32_e32 v43, vcc, 0, v63, vcc
	global_load_dwordx4 v[38:41], v[42:43], off offset:-4096
	s_nop 0
	global_load_dwordx4 v[42:45], v[42:43], off nt
	v_add_co_u32_e32 v50, vcc, s0, v62
	s_mov_b32 s0, 0xe000
	s_nop 0
	v_addc_co_u32_e32 v51, vcc, 0, v63, vcc
	global_load_dwordx4 v[46:49], v[50:51], off offset:-4096
	s_nop 0
	global_load_dwordx4 v[50:53], v[50:51], off nt
	v_add_co_u32_e32 v58, vcc, s0, v62
	s_mov_b32 s0, 0xf000
	s_nop 0
	v_addc_co_u32_e32 v59, vcc, 0, v63, vcc
	global_load_dwordx4 v[54:57], v[58:59], off offset:-4096
	s_nop 0
	global_load_dwordx4 v[58:61], v[58:59], off nt
	v_add_co_u32_e32 v62, vcc, s0, v62
	v_add_u32_e32 v0, 0x410, v69
	s_nop 0
	v_addc_co_u32_e32 v63, vcc, 0, v63, vcc
	global_load_dwordx4 v[62:65], v[62:63], off nt
	s_lshl_b32 s0, s11, 1
	v_readlane_b32 s37, v253, 2
	v_readlane_b32 s38, v253, 3
	v_readlane_b32 s39, v253, 4
	v_readlane_b32 s40, v253, 5
	v_readlane_b32 s41, v253, 6
	v_readlane_b32 s42, v253, 7
	v_readlane_b32 s43, v253, 8
	v_readlane_b32 s44, v253, 9
	v_readlane_b32 s45, v253, 10
	v_readlane_b32 s46, v253, 11
	v_readlane_b32 s47, v253, 12
	v_readlane_b32 s48, v253, 13
	v_readlane_b32 s49, v253, 14
	s_waitcnt vmcnt(0)
	ds_write2_b32 v69, v2, v3 offset1:1
	ds_write2_b32 v69, v4, v5 offset0:2 offset1:3
	v_lshl_add_u64 v[2:3], v[72:73], 0, s[0:1]
	ds_write2_b32 v0, v6, v7 offset1:1
	v_add_u32_e32 v0, 0x418, v69
	ds_write2_b32 v0, v8, v9 offset1:1
	v_add_u32_e32 v0, 0x820, v69
	ds_write2_b32 v0, v10, v11 offset1:1
	v_add_u32_e32 v0, 0x828, v69
	ds_write2_b32 v0, v12, v13 offset1:1
	v_add_u32_e32 v0, 0xc30, v69
	ds_write2_b32 v0, v14, v15 offset1:1
	v_add_u32_e32 v0, 0xc38, v69
	ds_write2_b32 v0, v16, v17 offset1:1
	v_add_u32_e32 v0, 0x1040, v69
	ds_write2_b32 v0, v18, v19 offset1:1
	v_add_u32_e32 v0, 0x1048, v69
	ds_write2_b32 v0, v20, v21 offset1:1
	v_add_u32_e32 v0, 0x1450, v69
	ds_write2_b32 v0, v22, v23 offset1:1
	v_add_u32_e32 v0, 0x1458, v69
	ds_write2_b32 v0, v24, v25 offset1:1
	v_add_u32_e32 v0, 0x1860, v69
	ds_write2_b32 v0, v26, v27 offset1:1
	v_add_u32_e32 v0, 0x1868, v69
	ds_write2_b32 v0, v28, v29 offset1:1
	v_add_u32_e32 v0, 0x1c70, v69
	ds_write2_b32 v0, v30, v31 offset1:1
	v_add_u32_e32 v0, 0x1c78, v69
	ds_write2_b32 v0, v32, v33 offset1:1
	v_add_u32_e32 v0, 0x2080, v69
	ds_write2_b32 v0, v34, v35 offset1:1
	v_add_u32_e32 v0, 0x2088, v69
	ds_write2_b32 v0, v36, v37 offset1:1
	v_add_u32_e32 v0, 0x2490, v69
	ds_write2_b32 v0, v38, v39 offset1:1
	v_add_u32_e32 v0, 0x2498, v69
	ds_write2_b32 v0, v40, v41 offset1:1
	v_add_u32_e32 v0, 0x28a0, v69
	ds_write2_b32 v0, v42, v43 offset1:1
	v_add_u32_e32 v0, 0x28a8, v69
	ds_write2_b32 v0, v44, v45 offset1:1
	v_add_u32_e32 v0, 0x2cb0, v69
	ds_write2_b32 v0, v46, v47 offset1:1
	v_add_u32_e32 v0, 0x2cb8, v69
	ds_write2_b32 v0, v48, v49 offset1:1
	v_add_u32_e32 v0, 0x30c0, v69
	ds_write2_b32 v0, v50, v51 offset1:1
	v_add_u32_e32 v0, 0x30c8, v69
	ds_write2_b32 v0, v52, v53 offset1:1
	v_add_u32_e32 v0, 0x34d0, v69
	ds_write2_b32 v0, v54, v55 offset1:1
	v_add_u32_e32 v0, 0x34d8, v69
	ds_write2_b32 v0, v56, v57 offset1:1
	v_add_u32_e32 v0, 0x38e0, v69
	ds_write2_b32 v0, v58, v59 offset1:1
	v_add_u32_e32 v0, 0x38e8, v69
	ds_write2_b32 v0, v60, v61 offset1:1
	v_add_u32_e32 v0, 0x3cf0, v69
	ds_write2_b32 v0, v62, v63 offset1:1
	v_add_u32_e32 v0, 0x3cf8, v69
	ds_write2_b32 v0, v64, v65 offset1:1
	s_waitcnt lgkmcnt(0)
	v_add_u32_e32 v26, 0x400, v87
	ds_read2_b32 v[8:9], v87 offset0:65 offset1:73
	ds_read2_b32 v[10:11], v87 offset1:8
	ds_read2_b32 v[12:13], v87 offset0:130 offset1:138
	ds_read2_b32 v[14:15], v87 offset0:195 offset1:203
	ds_read2_b32 v[16:17], v26 offset0:4 offset1:12
	ds_read2_b32 v[18:19], v26 offset0:69 offset1:77
	ds_read2_b32 v[20:21], v26 offset0:134 offset1:142
	ds_read2_b32 v[22:23], v26 offset0:199 offset1:207
	v_or_b32_e32 v0, s10, v86
	v_lshlrev_b64 v[24:25], 9, v[0:1]
	s_waitcnt lgkmcnt(6)
	v_cvt_pk_bf16_f32 v4, v10, v8
	s_waitcnt lgkmcnt(4)
	v_cvt_pk_bf16_f32 v5, v12, v14
	s_waitcnt lgkmcnt(2)
	v_cvt_pk_bf16_f32 v6, v16, v18
	s_waitcnt lgkmcnt(0)
	v_cvt_pk_bf16_f32 v7, v20, v22
	v_lshl_add_u64 v[24:25], v[2:3], 0, v[24:25]
	v_or_b32_e32 v0, s10, v88
	global_store_dwordx4 v[24:25], v[4:7], off
	s_nop 1
	v_cvt_pk_bf16_f32 v4, v11, v9
	v_lshlrev_b64 v[8:9], 9, v[0:1]
	v_cvt_pk_bf16_f32 v5, v13, v15
	v_cvt_pk_bf16_f32 v6, v17, v19
	v_cvt_pk_bf16_f32 v7, v21, v23
	v_lshl_add_u64 v[8:9], v[2:3], 0, v[8:9]
	global_store_dwordx4 v[8:9], v[4:7], off
	ds_read2_b32 v[8:9], v87 offset0:81 offset1:89
	ds_read2_b32 v[10:11], v87 offset0:16 offset1:24
	ds_read2_b32 v[12:13], v87 offset0:146 offset1:154
	ds_read2_b32 v[14:15], v87 offset0:211 offset1:219
	ds_read2_b32 v[16:17], v26 offset0:20 offset1:28
	ds_read2_b32 v[18:19], v26 offset0:85 offset1:93
	ds_read2_b32 v[20:21], v26 offset0:150 offset1:158
	ds_read2_b32 v[22:23], v26 offset0:215 offset1:223
	v_or_b32_e32 v0, s10, v89
	v_lshlrev_b64 v[24:25], 9, v[0:1]
	s_waitcnt lgkmcnt(6)
	v_cvt_pk_bf16_f32 v4, v10, v8
	s_waitcnt lgkmcnt(4)
	v_cvt_pk_bf16_f32 v5, v12, v14
	s_waitcnt lgkmcnt(2)
	v_cvt_pk_bf16_f32 v6, v16, v18
	s_waitcnt lgkmcnt(0)
	v_cvt_pk_bf16_f32 v7, v20, v22
	v_lshl_add_u64 v[24:25], v[2:3], 0, v[24:25]
	v_or_b32_e32 v0, s10, v90
	global_store_dwordx4 v[24:25], v[4:7], off
	s_nop 1
	v_cvt_pk_bf16_f32 v4, v11, v9
	v_lshlrev_b64 v[8:9], 9, v[0:1]
	v_cvt_pk_bf16_f32 v5, v13, v15
	v_cvt_pk_bf16_f32 v6, v17, v19
	v_cvt_pk_bf16_f32 v7, v21, v23
	v_lshl_add_u64 v[8:9], v[2:3], 0, v[8:9]
	global_store_dwordx4 v[8:9], v[4:7], off
	ds_read2_b32 v[8:9], v87 offset0:32 offset1:40
	ds_read2_b32 v[10:11], v87 offset0:97 offset1:105
	ds_read2_b32 v[12:13], v87 offset0:162 offset1:170
	ds_read2_b32 v[14:15], v87 offset0:227 offset1:235
	ds_read2_b32 v[16:17], v26 offset0:36 offset1:44
	ds_read2_b32 v[18:19], v26 offset0:101 offset1:109
	ds_read2_b32 v[20:21], v26 offset0:166 offset1:174
	ds_read2_b32 v[22:23], v26 offset0:231 offset1:239
	v_or_b32_e32 v0, s10, v91
	v_lshlrev_b64 v[24:25], 9, v[0:1]
	s_waitcnt lgkmcnt(6)
	v_cvt_pk_bf16_f32 v4, v8, v10
	s_waitcnt lgkmcnt(4)
	v_cvt_pk_bf16_f32 v5, v12, v14
	s_waitcnt lgkmcnt(2)
	v_cvt_pk_bf16_f32 v6, v16, v18
	s_waitcnt lgkmcnt(0)
	v_cvt_pk_bf16_f32 v7, v20, v22
	v_lshl_add_u64 v[24:25], v[2:3], 0, v[24:25]
	v_or_b32_e32 v0, s10, v92
	global_store_dwordx4 v[24:25], v[4:7], off
	s_nop 1
	v_cvt_pk_bf16_f32 v4, v9, v11
	v_lshlrev_b64 v[8:9], 9, v[0:1]
	v_cvt_pk_bf16_f32 v5, v13, v15
	v_cvt_pk_bf16_f32 v6, v17, v19
	v_cvt_pk_bf16_f32 v7, v21, v23
	v_lshl_add_u64 v[8:9], v[2:3], 0, v[8:9]
	global_store_dwordx4 v[8:9], v[4:7], off
	ds_read2_b32 v[8:9], v87 offset0:48 offset1:56
	ds_read2_b32 v[10:11], v87 offset0:113 offset1:121
	ds_read2_b32 v[12:13], v87 offset0:178 offset1:186
	ds_read2_b32 v[14:15], v87 offset0:243 offset1:251
	ds_read2_b32 v[16:17], v26 offset0:52 offset1:60
	ds_read2_b32 v[18:19], v26 offset0:117 offset1:125
	ds_read2_b32 v[20:21], v26 offset0:182 offset1:190
	ds_read2_b32 v[22:23], v26 offset0:247 offset1:255
	v_or_b32_e32 v0, s10, v93
	v_lshlrev_b64 v[24:25], 9, v[0:1]
	s_waitcnt lgkmcnt(6)
	v_cvt_pk_bf16_f32 v4, v8, v10
	s_waitcnt lgkmcnt(4)
	v_cvt_pk_bf16_f32 v5, v12, v14
	s_waitcnt lgkmcnt(2)
	v_cvt_pk_bf16_f32 v6, v16, v18
	s_waitcnt lgkmcnt(0)
	v_cvt_pk_bf16_f32 v7, v20, v22
	v_lshl_add_u64 v[24:25], v[2:3], 0, v[24:25]
	v_or_b32_e32 v0, s10, v94
	global_store_dwordx4 v[24:25], v[4:7], off
	s_nop 1
	v_cvt_pk_bf16_f32 v4, v9, v11
	v_lshlrev_b64 v[8:9], 9, v[0:1]
	v_cvt_pk_bf16_f32 v5, v13, v15
	v_cvt_pk_bf16_f32 v6, v17, v19
	v_cvt_pk_bf16_f32 v7, v21, v23
	v_lshl_add_u64 v[2:3], v[2:3], 0, v[8:9]
	global_store_dwordx4 v[2:3], v[4:7], off
	s_waitcnt lgkmcnt(0)

.LBB0_872:
	s_andn2_b64 vcc, exec, s[10:11]
	s_cbranch_vccnz .LBB0_874
	s_and_b32 s0, s17, 0xfc0
	s_add_i32 s10, s0, 0xfffff400
	s_and_b32 s12, s7, 0x3c0
	v_or_b32_e32 v0, s10, v66
	s_lshl_b32 s0, s12, 2
	v_or_b32_e32 v4, 4, v0
	v_mov_b32_e32 v5, v1
	v_lshl_add_u64 v[62:63], v[78:79], 0, s[0:1]
	v_lshlrev_b64 v[2:3], 12, v[0:1]
	v_lshlrev_b64 v[4:5], 12, v[4:5]
	v_lshl_add_u64 v[2:3], v[62:63], 0, v[2:3]
	v_lshl_add_u64 v[6:7], v[62:63], 0, v[4:5]
	global_load_dwordx4 v[2:5], v[2:3], off nt
	s_nop 0
	global_load_dwordx4 v[6:9], v[6:7], off nt
	v_or_b32_e32 v10, 8, v0
	v_mov_b32_e32 v11, v1
	v_or_b32_e32 v12, 12, v0
	v_mov_b32_e32 v13, v1
	v_lshlrev_b64 v[10:11], 12, v[10:11]
	v_lshlrev_b64 v[12:13], 12, v[12:13]
	v_lshl_add_u64 v[10:11], v[62:63], 0, v[10:11]
	v_lshl_add_u64 v[14:15], v[62:63], 0, v[12:13]
	global_load_dwordx4 v[10:13], v[10:11], off nt
	s_nop 0
	global_load_dwordx4 v[14:17], v[14:15], off nt
	v_or_b32_e32 v18, 16, v0
	v_mov_b32_e32 v19, v1
	v_or_b32_e32 v20, 20, v0
	v_mov_b32_e32 v21, v1
	v_lshlrev_b64 v[18:19], 12, v[18:19]
	v_lshlrev_b64 v[20:21], 12, v[20:21]
	v_lshl_add_u64 v[18:19], v[62:63], 0, v[18:19]
	v_lshl_add_u64 v[22:23], v[62:63], 0, v[20:21]
	global_load_dwordx4 v[18:21], v[18:19], off nt
	s_nop 0
	global_load_dwordx4 v[22:25], v[22:23], off nt
	v_or_b32_e32 v26, 24, v0
	v_mov_b32_e32 v27, v1
	v_or_b32_e32 v28, 28, v0
	v_mov_b32_e32 v29, v1
	v_lshlrev_b64 v[26:27], 12, v[26:27]
	v_lshlrev_b64 v[28:29], 12, v[28:29]
	v_lshl_add_u64 v[26:27], v[62:63], 0, v[26:27]
	v_lshl_add_u64 v[30:31], v[62:63], 0, v[28:29]
	global_load_dwordx4 v[26:29], v[26:27], off nt
	s_nop 0
	global_load_dwordx4 v[30:33], v[30:31], off nt
	v_or_b32_e32 v34, 32, v0
	v_mov_b32_e32 v35, v1
	v_or_b32_e32 v36, 36, v0
	v_mov_b32_e32 v37, v1
	v_lshlrev_b64 v[34:35], 12, v[34:35]
	v_lshlrev_b64 v[36:37], 12, v[36:37]
	v_lshl_add_u64 v[34:35], v[62:63], 0, v[34:35]
	v_lshl_add_u64 v[38:39], v[62:63], 0, v[36:37]
	global_load_dwordx4 v[34:37], v[34:35], off nt
	s_nop 0
	global_load_dwordx4 v[38:41], v[38:39], off nt
	v_or_b32_e32 v42, 40, v0
	v_mov_b32_e32 v43, v1
	v_or_b32_e32 v44, 44, v0
	v_mov_b32_e32 v45, v1
	v_lshlrev_b64 v[42:43], 12, v[42:43]
	v_lshlrev_b64 v[44:45], 12, v[44:45]
	v_lshl_add_u64 v[42:43], v[62:63], 0, v[42:43]
	v_lshl_add_u64 v[46:47], v[62:63], 0, v[44:45]
	global_load_dwordx4 v[42:45], v[42:43], off nt
	s_nop 0
	global_load_dwordx4 v[46:49], v[46:47], off nt
	v_or_b32_e32 v50, 48, v0
	v_mov_b32_e32 v51, v1
	v_lshlrev_b64 v[50:51], 12, v[50:51]
	v_lshl_add_u64 v[50:51], v[62:63], 0, v[50:51]
	v_or_b32_e32 v54, 52, v0
	v_mov_b32_e32 v55, v1
	global_load_dwordx4 v[50:53], v[50:51], off nt
	v_lshlrev_b64 v[54:55], 12, v[54:55]
	v_lshl_add_u64 v[54:55], v[62:63], 0, v[54:55]
	v_or_b32_e32 v58, 56, v0
	v_mov_b32_e32 v59, v1
	global_load_dwordx4 v[54:57], v[54:55], off nt
	v_lshlrev_b64 v[58:59], 12, v[58:59]
	v_lshl_add_u64 v[58:59], v[62:63], 0, v[58:59]
	v_or_b32_e32 v0, 60, v0
	global_load_dwordx4 v[58:61], v[58:59], off nt
	v_lshlrev_b64 v[64:65], 12, v[0:1]
	v_lshl_add_u64 v[62:63], v[62:63], 0, v[64:65]
	global_load_dwordx4 v[62:65], v[62:63], off nt
	v_add_u32_e32 v0, 0x410, v69
	s_mov_b32 s11, s1
	s_waitcnt vmcnt(0)
	ds_write2_b32 v69, v2, v3 offset1:1
	ds_write2_b32 v69, v4, v5 offset0:2 offset1:3
	ds_write2_b32 v0, v6, v7 offset1:1
	v_add_u32_e32 v0, 0x418, v69
	ds_write2_b32 v0, v8, v9 offset1:1
	v_add_u32_e32 v0, 0x820, v69
	ds_write2_b32 v0, v10, v11 offset1:1
	v_add_u32_e32 v0, 0x828, v69
	ds_write2_b32 v0, v12, v13 offset1:1
	v_add_u32_e32 v0, 0xc30, v69
	ds_write2_b32 v0, v14, v15 offset1:1
	v_add_u32_e32 v0, 0xc38, v69
	ds_write2_b32 v0, v16, v17 offset1:1
	v_add_u32_e32 v0, 0x1040, v69
	ds_write2_b32 v0, v18, v19 offset1:1
	v_add_u32_e32 v0, 0x1048, v69
	ds_write2_b32 v0, v20, v21 offset1:1
	v_add_u32_e32 v0, 0x1450, v69
	ds_write2_b32 v0, v22, v23 offset1:1
	v_add_u32_e32 v0, 0x1458, v69
	ds_write2_b32 v0, v24, v25 offset1:1
	v_add_u32_e32 v0, 0x1860, v69
	v_lshl_add_u64 v[22:23], s[10:11], 1, v[74:75]
	ds_write2_b32 v0, v26, v27 offset1:1
	v_add_u32_e32 v0, 0x1868, v69
	ds_write2_b32 v0, v28, v29 offset1:1
	v_add_u32_e32 v0, 0x1c70, v69
	ds_write2_b32 v0, v30, v31 offset1:1
	v_add_u32_e32 v0, 0x1c78, v69
	ds_write2_b32 v0, v32, v33 offset1:1
	v_add_u32_e32 v0, 0x2080, v69
	v_add_u32_e32 v26, 0x400, v87
	ds_write2_b32 v0, v34, v35 offset1:1
	v_add_u32_e32 v0, 0x2088, v69
	ds_write2_b32 v0, v36, v37 offset1:1
	v_add_u32_e32 v0, 0x2490, v69
	ds_write2_b32 v0, v38, v39 offset1:1
	v_add_u32_e32 v0, 0x2498, v69
	ds_write2_b32 v0, v40, v41 offset1:1
	v_add_u32_e32 v0, 0x28a0, v69
	ds_write2_b32 v0, v42, v43 offset1:1
	v_add_u32_e32 v0, 0x28a8, v69
	ds_write2_b32 v0, v44, v45 offset1:1
	v_add_u32_e32 v0, 0x2cb0, v69
	ds_write2_b32 v0, v46, v47 offset1:1
	v_add_u32_e32 v0, 0x2cb8, v69
	ds_write2_b32 v0, v48, v49 offset1:1
	v_add_u32_e32 v0, 0x30c0, v69
	ds_write2_b32 v0, v50, v51 offset1:1
	v_add_u32_e32 v0, 0x30c8, v69
	ds_write2_b32 v0, v52, v53 offset1:1
	v_add_u32_e32 v0, 0x34d0, v69
	ds_write2_b32 v0, v54, v55 offset1:1
	v_add_u32_e32 v0, 0x34d8, v69
	ds_write2_b32 v0, v56, v57 offset1:1
	v_add_u32_e32 v0, 0x38e0, v69
	ds_write2_b32 v0, v58, v59 offset1:1
	v_add_u32_e32 v0, 0x38e8, v69
	ds_write2_b32 v0, v60, v61 offset1:1
	v_add_u32_e32 v0, 0x3cf0, v69
	ds_write2_b32 v0, v62, v63 offset1:1
	v_add_u32_e32 v0, 0x3cf8, v69
	ds_write2_b32 v0, v64, v65 offset1:1
	s_waitcnt lgkmcnt(0)
	ds_read2_b32 v[6:7], v87 offset0:65 offset1:73
	ds_read2_b32 v[8:9], v87 offset1:8
	ds_read2_b32 v[10:11], v87 offset0:130 offset1:138
	ds_read2_b32 v[12:13], v87 offset0:195 offset1:203
	ds_read2_b32 v[14:15], v26 offset0:4 offset1:12
	ds_read2_b32 v[16:17], v26 offset0:69 offset1:77
	ds_read2_b32 v[18:19], v26 offset0:134 offset1:142
	ds_read2_b32 v[20:21], v26 offset0:199 offset1:207
	v_or_b32_e32 v0, s12, v86
	v_lshlrev_b32_e32 v0, 11, v0
	s_waitcnt lgkmcnt(6)
	v_cvt_pk_bf16_f32 v2, v8, v6
	s_waitcnt lgkmcnt(4)
	v_cvt_pk_bf16_f32 v3, v10, v12
	s_waitcnt lgkmcnt(2)
	v_cvt_pk_bf16_f32 v4, v14, v16
	s_waitcnt lgkmcnt(0)
	v_cvt_pk_bf16_f32 v5, v18, v20
	v_lshl_add_u64 v[24:25], v[22:23], 0, v[0:1]
	global_store_dwordx4 v[24:25], v[2:5], off
	v_or_b32_e32 v0, s12, v88
	v_lshlrev_b32_e32 v0, 11, v0
	v_cvt_pk_bf16_f32 v2, v9, v7
	v_cvt_pk_bf16_f32 v3, v11, v13
	v_cvt_pk_bf16_f32 v4, v15, v17
	v_cvt_pk_bf16_f32 v5, v19, v21
	ds_read2_b32 v[8:9], v87 offset0:81 offset1:89
	ds_read2_b32 v[10:11], v87 offset0:16 offset1:24
	ds_read2_b32 v[12:13], v87 offset0:146 offset1:154
	ds_read2_b32 v[14:15], v87 offset0:211 offset1:219
	ds_read2_b32 v[16:17], v26 offset0:20 offset1:28
	ds_read2_b32 v[18:19], v26 offset0:85 offset1:93
	ds_read2_b32 v[20:21], v26 offset0:150 offset1:158
	ds_read2_b32 v[24:25], v26 offset0:215 offset1:223
	v_lshl_add_u64 v[6:7], v[22:23], 0, v[0:1]
	v_or_b32_e32 v0, s12, v89
	v_lshlrev_b32_e32 v0, 11, v0
	global_store_dwordx4 v[6:7], v[2:5], off
	v_lshl_add_u64 v[6:7], v[22:23], 0, v[0:1]
	v_or_b32_e32 v0, s12, v90
	s_waitcnt lgkmcnt(6)
	v_cvt_pk_bf16_f32 v2, v10, v8
	s_waitcnt lgkmcnt(4)
	v_cvt_pk_bf16_f32 v3, v12, v14
	s_waitcnt lgkmcnt(2)
	v_cvt_pk_bf16_f32 v4, v16, v18
	s_waitcnt lgkmcnt(0)
	v_cvt_pk_bf16_f32 v5, v20, v24
	global_store_dwordx4 v[6:7], v[2:5], off
	v_lshlrev_b32_e32 v0, 11, v0
	v_lshl_add_u64 v[6:7], v[22:23], 0, v[0:1]
	v_cvt_pk_bf16_f32 v2, v11, v9
	v_cvt_pk_bf16_f32 v3, v13, v15
	v_cvt_pk_bf16_f32 v4, v17, v19
	v_cvt_pk_bf16_f32 v5, v21, v25
	ds_read2_b32 v[8:9], v87 offset0:32 offset1:40
	ds_read2_b32 v[10:11], v87 offset0:97 offset1:105
	ds_read2_b32 v[12:13], v87 offset0:162 offset1:170
	ds_read2_b32 v[14:15], v87 offset0:227 offset1:235
	ds_read2_b32 v[16:17], v26 offset0:36 offset1:44
	ds_read2_b32 v[18:19], v26 offset0:101 offset1:109
	ds_read2_b32 v[20:21], v26 offset0:166 offset1:174
	ds_read2_b32 v[24:25], v26 offset0:231 offset1:239
	v_or_b32_e32 v0, s12, v91
	v_lshlrev_b32_e32 v0, 11, v0
	global_store_dwordx4 v[6:7], v[2:5], off
	v_lshl_add_u64 v[6:7], v[22:23], 0, v[0:1]
	v_or_b32_e32 v0, s12, v92
	s_waitcnt lgkmcnt(6)
	v_cvt_pk_bf16_f32 v2, v8, v10
	s_waitcnt lgkmcnt(4)
	v_cvt_pk_bf16_f32 v3, v12, v14
	s_waitcnt lgkmcnt(2)
	v_cvt_pk_bf16_f32 v4, v16, v18
	s_waitcnt lgkmcnt(0)
	v_cvt_pk_bf16_f32 v5, v20, v24
	global_store_dwordx4 v[6:7], v[2:5], off
	v_lshlrev_b32_e32 v0, 11, v0
	v_lshl_add_u64 v[6:7], v[22:23], 0, v[0:1]
	v_cvt_pk_bf16_f32 v2, v9, v11
	v_cvt_pk_bf16_f32 v3, v13, v15
	v_cvt_pk_bf16_f32 v4, v17, v19
	v_cvt_pk_bf16_f32 v5, v21, v25
	ds_read2_b32 v[8:9], v87 offset0:48 offset1:56
	ds_read2_b32 v[10:11], v87 offset0:113 offset1:121
	ds_read2_b32 v[12:13], v87 offset0:178 offset1:186
	ds_read2_b32 v[14:15], v87 offset0:243 offset1:251
	ds_read2_b32 v[16:17], v26 offset0:52 offset1:60
	ds_read2_b32 v[18:19], v26 offset0:117 offset1:125
	ds_read2_b32 v[20:21], v26 offset0:182 offset1:190
	ds_read2_b32 v[24:25], v26 offset0:247 offset1:255
	v_or_b32_e32 v0, s12, v93
	v_lshlrev_b32_e32 v0, 11, v0
	global_store_dwordx4 v[6:7], v[2:5], off
	v_lshl_add_u64 v[6:7], v[22:23], 0, v[0:1]
	v_or_b32_e32 v0, s12, v94
	s_waitcnt lgkmcnt(6)
	v_cvt_pk_bf16_f32 v2, v8, v10
	s_waitcnt lgkmcnt(4)
	v_cvt_pk_bf16_f32 v3, v12, v14
	s_waitcnt lgkmcnt(2)
	v_cvt_pk_bf16_f32 v4, v16, v18
	s_waitcnt lgkmcnt(0)
	v_cvt_pk_bf16_f32 v5, v20, v24
	v_lshlrev_b32_e32 v0, 11, v0
	global_store_dwordx4 v[6:7], v[2:5], off
	v_lshl_add_u64 v[6:7], v[22:23], 0, v[0:1]
	s_nop 0
	v_cvt_pk_bf16_f32 v2, v9, v11
	v_cvt_pk_bf16_f32 v3, v13, v15
	v_cvt_pk_bf16_f32 v4, v17, v19
	v_cvt_pk_bf16_f32 v5, v21, v25
	global_store_dwordx4 v[6:7], v[2:5], off
	s_waitcnt lgkmcnt(0)

.LBB0_875:
	s_andn2_b64 vcc, exec, s[10:11]
	s_cbranch_vccnz .LBB0_864
	s_mul_hi_i32 s0, s18, 0x2aaaaaab
	s_lshr_b32 s10, s0, 31
	s_ashr_i32 s0, s0, 3
	s_add_i32 s0, s0, s10
	s_lshl_b32 s12, s0, 6
	s_mulk_i32 s0, 0xf400
	s_add_i32 s10, s7, s0
	v_add_u32_e32 v0, s10, v68
	s_movk_i32 s0, 0xb18
	s_ashr_i32 s11, s10, 31
	v_mov_b32_e32 v58, 0
	v_cmp_gt_i32_e32 vcc, s0, v0
	v_or_b32_e32 v82, s12, v66
	v_lshl_add_u64 v[84:85], s[10:11], 2, v[80:81]
	v_mov_b32_e32 v62, 0
	v_mov_b32_e32 v63, v58
	v_mov_b32_e32 v64, 0
	v_mov_b32_e32 v65, 0
	s_and_saveexec_b64 s[14:15], vcc
	s_cbranch_execz .LBB0_878
	s_movk_i32 s0, 0x2c60
	v_mad_i64_i32 v[2:3], s[26:27], v82, s0, v[84:85]
	global_load_dwordx4 v[62:65], v[2:3], off nt
.LBB0_878:
	s_or_b64 exec, exec, s[14:15]
	v_mov_b32_e32 v59, 0
	v_mov_b32_e32 v60, 0
	v_mov_b32_e32 v61, 0
	s_and_saveexec_b64 s[14:15], vcc
	s_cbranch_execz .LBB0_880
	v_or_b32_e32 v0, 4, v82
	s_movk_i32 s0, 0x2c60
	v_mad_i64_i32 v[2:3], s[26:27], v0, s0, v[84:85]
	global_load_dwordx4 v[58:61], v[2:3], off nt
.LBB0_880:
	s_or_b64 exec, exec, s[14:15]
	v_mov_b32_e32 v50, 0
	v_mov_b32_e32 v54, 0
	v_mov_b32_e32 v55, 0
	v_mov_b32_e32 v56, 0
	v_mov_b32_e32 v57, 0
	s_and_saveexec_b64 s[14:15], vcc
	s_cbranch_execz .LBB0_882
	v_or_b32_e32 v0, 8, v82
	s_movk_i32 s0, 0x2c60
	v_mad_i64_i32 v[2:3], s[26:27], v0, s0, v[84:85]
	global_load_dwordx4 v[54:57], v[2:3], off nt
.LBB0_882:
	s_or_b64 exec, exec, s[14:15]
	v_mov_b32_e32 v51, 0
	v_mov_b32_e32 v52, 0
	v_mov_b32_e32 v53, 0
	s_and_saveexec_b64 s[14:15], vcc
	s_cbranch_execz .LBB0_884
	v_or_b32_e32 v0, 12, v82
	s_movk_i32 s0, 0x2c60
	v_mad_i64_i32 v[2:3], s[26:27], v0, s0, v[84:85]
	global_load_dwordx4 v[50:53], v[2:3], off nt
.LBB0_884:
	s_or_b64 exec, exec, s[14:15]
	v_mov_b32_e32 v42, 0
	v_mov_b32_e32 v46, 0
	v_mov_b32_e32 v47, 0
	v_mov_b32_e32 v48, 0
	v_mov_b32_e32 v49, 0
	s_and_saveexec_b64 s[14:15], vcc
	s_cbranch_execz .LBB0_886
	v_or_b32_e32 v0, 16, v82
	s_movk_i32 s0, 0x2c60
	v_mad_i64_i32 v[2:3], s[26:27], v0, s0, v[84:85]
	global_load_dwordx4 v[46:49], v[2:3], off nt
.LBB0_886:
	s_or_b64 exec, exec, s[14:15]
	v_mov_b32_e32 v43, 0
	v_mov_b32_e32 v44, 0
	v_mov_b32_e32 v45, 0
	s_and_saveexec_b64 s[14:15], vcc
	s_cbranch_execz .LBB0_888
	v_or_b32_e32 v0, 20, v82
	s_movk_i32 s0, 0x2c60
	v_mad_i64_i32 v[2:3], s[26:27], v0, s0, v[84:85]
	global_load_dwordx4 v[42:45], v[2:3], off nt
.LBB0_888:
	s_or_b64 exec, exec, s[14:15]
	v_mov_b32_e32 v34, 0
	v_mov_b32_e32 v38, 0
	v_mov_b32_e32 v39, 0
	v_mov_b32_e32 v40, 0
	v_mov_b32_e32 v41, 0
	s_and_saveexec_b64 s[14:15], vcc
	s_cbranch_execz .LBB0_890
	v_or_b32_e32 v0, 24, v82
	s_movk_i32 s0, 0x2c60
	v_mad_i64_i32 v[2:3], s[26:27], v0, s0, v[84:85]
	global_load_dwordx4 v[38:41], v[2:3], off nt
.LBB0_890:
	s_or_b64 exec, exec, s[14:15]
	v_mov_b32_e32 v35, 0
	v_mov_b32_e32 v36, 0
	v_mov_b32_e32 v37, 0
	s_and_saveexec_b64 s[14:15], vcc
	s_cbranch_execz .LBB0_892
	v_or_b32_e32 v0, 28, v82
	s_movk_i32 s0, 0x2c60
	v_mad_i64_i32 v[2:3], s[26:27], v0, s0, v[84:85]
	global_load_dwordx4 v[34:37], v[2:3], off nt
.LBB0_892:
	s_or_b64 exec, exec, s[14:15]
	v_mov_b32_e32 v26, 0
	v_mov_b32_e32 v30, 0
	v_mov_b32_e32 v31, 0
	v_mov_b32_e32 v32, 0
	v_mov_b32_e32 v33, 0
	s_and_saveexec_b64 s[14:15], vcc
	s_cbranch_execz .LBB0_894
	v_or_b32_e32 v0, 32, v82
	s_movk_i32 s0, 0x2c60
	v_mad_i64_i32 v[2:3], s[26:27], v0, s0, v[84:85]
	global_load_dwordx4 v[30:33], v[2:3], off nt
.LBB0_894:
	s_or_b64 exec, exec, s[14:15]
	v_mov_b32_e32 v27, 0
	v_mov_b32_e32 v28, 0
	v_mov_b32_e32 v29, 0
	s_and_saveexec_b64 s[14:15], vcc
	s_cbranch_execz .LBB0_896
	v_or_b32_e32 v0, 36, v82
	s_movk_i32 s0, 0x2c60
	v_mad_i64_i32 v[2:3], s[26:27], v0, s0, v[84:85]
	global_load_dwordx4 v[26:29], v[2:3], off nt
.LBB0_896:
	s_or_b64 exec, exec, s[14:15]
	v_mov_b32_e32 v18, 0
	v_mov_b32_e32 v22, 0
	v_mov_b32_e32 v23, 0
	v_mov_b32_e32 v24, 0
	v_mov_b32_e32 v25, 0
	s_and_saveexec_b64 s[14:15], vcc
	s_cbranch_execz .LBB0_898
	v_or_b32_e32 v0, 40, v82
	s_movk_i32 s0, 0x2c60
	v_mad_i64_i32 v[2:3], s[26:27], v0, s0, v[84:85]
	global_load_dwordx4 v[22:25], v[2:3], off nt
.LBB0_898:
	s_or_b64 exec, exec, s[14:15]
	v_mov_b32_e32 v19, 0
	v_mov_b32_e32 v20, 0
	v_mov_b32_e32 v21, 0
	s_and_saveexec_b64 s[14:15], vcc
	s_cbranch_execz .LBB0_900
	v_or_b32_e32 v0, 44, v82
	s_movk_i32 s0, 0x2c60
	v_mad_i64_i32 v[2:3], s[26:27], v0, s0, v[84:85]
	global_load_dwordx4 v[18:21], v[2:3], off nt
.LBB0_900:
	s_or_b64 exec, exec, s[14:15]
	v_mov_b32_e32 v10, 0
	v_mov_b32_e32 v14, 0
	v_mov_b32_e32 v15, 0
	v_mov_b32_e32 v16, 0
	v_mov_b32_e32 v17, 0
	s_and_saveexec_b64 s[14:15], vcc
	s_cbranch_execz .LBB0_902
	v_or_b32_e32 v0, 48, v82
	s_movk_i32 s0, 0x2c60
	v_mad_i64_i32 v[2:3], s[26:27], v0, s0, v[84:85]
	global_load_dwordx4 v[14:17], v[2:3], off nt
.LBB0_902:
	s_or_b64 exec, exec, s[14:15]
	v_mov_b32_e32 v11, 0
	v_mov_b32_e32 v12, 0
	v_mov_b32_e32 v13, 0
	s_and_saveexec_b64 s[14:15], vcc
	s_cbranch_execz .LBB0_904
	v_or_b32_e32 v0, 52, v82
	s_movk_i32 s0, 0x2c60
	v_mad_i64_i32 v[2:3], s[26:27], v0, s0, v[84:85]
	global_load_dwordx4 v[10:13], v[2:3], off nt
.LBB0_904:
	s_or_b64 exec, exec, s[14:15]
	v_mov_b32_e32 v2, 0
	v_mov_b32_e32 v6, 0
	v_mov_b32_e32 v7, 0
	v_mov_b32_e32 v8, 0
	v_mov_b32_e32 v9, 0
	s_and_saveexec_b64 s[14:15], vcc
	s_cbranch_execz .LBB0_906
	v_or_b32_e32 v0, 56, v82
	s_movk_i32 s0, 0x2c60
	v_mad_i64_i32 v[4:5], s[26:27], v0, s0, v[84:85]
	global_load_dwordx4 v[6:9], v[4:5], off nt
.LBB0_906:
	s_or_b64 exec, exec, s[14:15]
	v_mov_b32_e32 v3, 0
	v_mov_b32_e32 v4, 0
	v_mov_b32_e32 v5, 0
	s_and_saveexec_b64 s[14:15], vcc
	s_cbranch_execz .LBB0_908
	v_or_b32_e32 v0, 60, v82
	s_movk_i32 s0, 0x2c60
	v_mad_i64_i32 v[2:3], s[26:27], v0, s0, v[84:85]
	global_load_dwordx4 v[2:5], v[2:3], off nt

.LBB0_950:
	s_mov_b64 s[10:11], -1
	s_cmpk_gt_i32 s8, 0x57f
	v_add_u32_e32 v90, 0x400, v77
	s_cbranch_scc0 .LBB0_952
	s_and_b32 s0, s6, 0x7fffffc0
	s_add_i32 s10, s0, 0xffffea00
	s_and_b32 s12, s9, 0x3c0
	v_or_b32_e32 v62, s10, v66
	s_lshl_b32 s0, s12, 2
	v_mov_b32_e32 v63, v1
	v_or_b32_e32 v4, 4, v62
	v_mov_b32_e32 v5, v1
	v_lshl_add_u64 v[64:65], v[72:73], 0, s[0:1]
	v_lshlrev_b64 v[2:3], 12, v[62:63]
	v_lshlrev_b64 v[4:5], 12, v[4:5]
	v_lshl_add_u64 v[2:3], v[64:65], 0, v[2:3]
	v_lshl_add_u64 v[6:7], v[64:65], 0, v[4:5]
	global_load_dwordx4 v[2:5], v[2:3], off nt
	s_nop 0
	global_load_dwordx4 v[6:9], v[6:7], off nt
	v_or_b32_e32 v10, 8, v62
	v_mov_b32_e32 v11, v1
	v_or_b32_e32 v12, 12, v62
	v_mov_b32_e32 v13, v1
	v_lshlrev_b64 v[10:11], 12, v[10:11]
	v_lshlrev_b64 v[12:13], 12, v[12:13]
	v_lshl_add_u64 v[10:11], v[64:65], 0, v[10:11]
	v_lshl_add_u64 v[14:15], v[64:65], 0, v[12:13]
	global_load_dwordx4 v[10:13], v[10:11], off nt
	s_nop 0
	global_load_dwordx4 v[14:17], v[14:15], off nt
	v_or_b32_e32 v18, 16, v62
	v_mov_b32_e32 v19, v1
	v_or_b32_e32 v20, 20, v62
	v_mov_b32_e32 v21, v1
	v_lshlrev_b64 v[18:19], 12, v[18:19]
	v_lshlrev_b64 v[20:21], 12, v[20:21]
	v_lshl_add_u64 v[18:19], v[64:65], 0, v[18:19]
	v_lshl_add_u64 v[22:23], v[64:65], 0, v[20:21]
	global_load_dwordx4 v[18:21], v[18:19], off nt
	s_nop 0
	global_load_dwordx4 v[22:25], v[22:23], off nt
	v_or_b32_e32 v26, 24, v62
	v_mov_b32_e32 v27, v1
	v_or_b32_e32 v28, 28, v62
	v_mov_b32_e32 v29, v1
	v_lshlrev_b64 v[26:27], 12, v[26:27]
	v_lshlrev_b64 v[28:29], 12, v[28:29]
	v_lshl_add_u64 v[26:27], v[64:65], 0, v[26:27]
	v_lshl_add_u64 v[30:31], v[64:65], 0, v[28:29]
	global_load_dwordx4 v[26:29], v[26:27], off nt
	s_nop 0
	global_load_dwordx4 v[30:33], v[30:31], off nt
	v_or_b32_e32 v34, 32, v62
	v_mov_b32_e32 v35, v1
	v_or_b32_e32 v36, 36, v62
	v_mov_b32_e32 v37, v1
	v_lshlrev_b64 v[34:35], 12, v[34:35]
	v_lshlrev_b64 v[36:37], 12, v[36:37]
	v_lshl_add_u64 v[34:35], v[64:65], 0, v[34:35]
	v_lshl_add_u64 v[38:39], v[64:65], 0, v[36:37]
	global_load_dwordx4 v[34:37], v[34:35], off nt
	s_nop 0
	global_load_dwordx4 v[38:41], v[38:39], off nt
	v_or_b32_e32 v42, 40, v62
	v_mov_b32_e32 v43, v1
	v_or_b32_e32 v44, 44, v62
	v_mov_b32_e32 v45, v1
	v_lshlrev_b64 v[42:43], 12, v[42:43]
	v_lshlrev_b64 v[44:45], 12, v[44:45]
	v_lshl_add_u64 v[42:43], v[64:65], 0, v[42:43]
	v_lshl_add_u64 v[46:47], v[64:65], 0, v[44:45]
	global_load_dwordx4 v[42:45], v[42:43], off nt
	s_nop 0
	global_load_dwordx4 v[46:49], v[46:47], off nt
	v_or_b32_e32 v50, 48, v62
	v_mov_b32_e32 v51, v1
	v_lshlrev_b64 v[50:51], 12, v[50:51]
	v_lshl_add_u64 v[50:51], v[64:65], 0, v[50:51]
	v_or_b32_e32 v54, 52, v62
	v_mov_b32_e32 v55, v1
	global_load_dwordx4 v[50:53], v[50:51], off nt
	v_lshlrev_b64 v[54:55], 12, v[54:55]
	v_lshl_add_u64 v[54:55], v[64:65], 0, v[54:55]
	v_or_b32_e32 v58, 56, v62
	v_mov_b32_e32 v59, v1
	global_load_dwordx4 v[54:57], v[54:55], off nt
	v_lshlrev_b64 v[58:59], 12, v[58:59]
	v_lshl_add_u64 v[58:59], v[64:65], 0, v[58:59]
	v_or_b32_e32 v62, 60, v62
	global_load_dwordx4 v[58:61], v[58:59], off nt
	v_lshlrev_b64 v[62:63], 12, v[62:63]
	v_lshl_add_u64 v[62:63], v[64:65], 0, v[62:63]
	global_load_dwordx4 v[62:65], v[62:63], off nt
	s_mov_b32 s11, s1
	s_waitcnt vmcnt(0)
	ds_write2_b32 v87, v2, v3 offset1:1
	ds_write2_b32 v87, v4, v5 offset0:2 offset1:3
	v_add_u32_e32 v2, 0x410, v87
	ds_write2_b32 v2, v6, v7 offset1:1
	v_add_u32_e32 v2, 0x418, v87
	ds_write2_b32 v2, v8, v9 offset1:1
	v_add_u32_e32 v2, 0x820, v87
	ds_write2_b32 v2, v10, v11 offset1:1
	v_add_u32_e32 v2, 0x828, v87
	ds_write2_b32 v2, v12, v13 offset1:1
	v_add_u32_e32 v2, 0xc30, v87
	ds_write2_b32 v2, v14, v15 offset1:1
	v_add_u32_e32 v2, 0xc38, v87
	ds_write2_b32 v2, v16, v17 offset1:1
	v_add_u32_e32 v2, 0x1040, v87
	ds_write2_b32 v2, v18, v19 offset1:1
	v_add_u32_e32 v2, 0x1048, v87
	ds_write2_b32 v2, v20, v21 offset1:1
	v_add_u32_e32 v2, 0x1450, v87
	ds_write2_b32 v2, v22, v23 offset1:1
	v_add_u32_e32 v2, 0x1458, v87
	ds_write2_b32 v2, v24, v25 offset1:1
	v_add_u32_e32 v2, 0x1860, v87
	v_lshl_add_u64 v[22:23], s[10:11], 1, v[68:69]
	ds_write2_b32 v2, v26, v27 offset1:1
	v_add_u32_e32 v2, 0x1868, v87
	ds_write2_b32 v2, v28, v29 offset1:1
	v_add_u32_e32 v2, 0x1c70, v87
	ds_write2_b32 v2, v30, v31 offset1:1
	v_add_u32_e32 v2, 0x1c78, v87
	ds_write2_b32 v2, v32, v33 offset1:1
	v_add_u32_e32 v2, 0x2080, v87
	v_mov_b32_e32 v25, v1
	ds_write2_b32 v2, v34, v35 offset1:1
	v_add_u32_e32 v2, 0x2088, v87
	ds_write2_b32 v2, v36, v37 offset1:1
	v_add_u32_e32 v2, 0x2490, v87
	ds_write2_b32 v2, v38, v39 offset1:1
	v_add_u32_e32 v2, 0x2498, v87
	ds_write2_b32 v2, v40, v41 offset1:1
	v_add_u32_e32 v2, 0x28a0, v87
	s_mov_b64 s[10:11], 0
	ds_write2_b32 v2, v42, v43 offset1:1
	v_add_u32_e32 v2, 0x28a8, v87
	ds_write2_b32 v2, v44, v45 offset1:1
	v_add_u32_e32 v2, 0x2cb0, v87
	ds_write2_b32 v2, v46, v47 offset1:1
	v_add_u32_e32 v2, 0x2cb8, v87
	ds_write2_b32 v2, v48, v49 offset1:1
	v_add_u32_e32 v2, 0x30c0, v87
	ds_write2_b32 v2, v50, v51 offset1:1
	v_add_u32_e32 v2, 0x30c8, v87
	ds_write2_b32 v2, v52, v53 offset1:1
	v_add_u32_e32 v2, 0x34d0, v87
	ds_write2_b32 v2, v54, v55 offset1:1
	v_add_u32_e32 v2, 0x34d8, v87
	ds_write2_b32 v2, v56, v57 offset1:1
	v_add_u32_e32 v2, 0x38e0, v87
	ds_write2_b32 v2, v58, v59 offset1:1
	v_add_u32_e32 v2, 0x38e8, v87
	ds_write2_b32 v2, v60, v61 offset1:1
	v_add_u32_e32 v2, 0x3cf0, v87
	ds_write2_b32 v2, v62, v63 offset1:1
	v_add_u32_e32 v2, 0x3cf8, v87
	ds_write2_b32 v2, v64, v65 offset1:1
	s_waitcnt lgkmcnt(0)
	ds_read2_b32 v[6:7], v77 offset0:65 offset1:73
	ds_read2_b32 v[8:9], v77 offset1:8
	ds_read2_b32 v[10:11], v77 offset0:130 offset1:138
	ds_read2_b32 v[12:13], v77 offset0:195 offset1:203
	ds_read2_b32 v[14:15], v90 offset0:4 offset1:12
	ds_read2_b32 v[16:17], v90 offset0:69 offset1:77
	ds_read2_b32 v[18:19], v90 offset0:134 offset1:142
	ds_read2_b32 v[20:21], v90 offset0:199 offset1:207
	s_waitcnt lgkmcnt(6)
	v_cvt_pk_bf16_f32 v2, v8, v6
	v_or_b32_e32 v6, s12, v76
	v_mul_u32_u24_e32 v6, 0xb00, v6
	v_lshlrev_b32_e32 v24, 1, v6
	s_waitcnt lgkmcnt(4)
	v_cvt_pk_bf16_f32 v3, v10, v12
	s_waitcnt lgkmcnt(2)
	v_cvt_pk_bf16_f32 v4, v14, v16
	s_waitcnt lgkmcnt(0)
	v_cvt_pk_bf16_f32 v5, v18, v20
	v_lshl_add_u64 v[24:25], v[22:23], 0, v[24:25]
	v_or_b32_e32 v6, s12, v78
	global_store_dwordx4 v[24:25], v[2:5], off
	v_mul_u32_u24_e32 v6, 0xb00, v6
	v_lshlrev_b32_e32 v6, 1, v6
	v_cvt_pk_bf16_f32 v2, v9, v7
	v_cvt_pk_bf16_f32 v3, v11, v13
	v_cvt_pk_bf16_f32 v4, v15, v17
	v_cvt_pk_bf16_f32 v5, v19, v21
	v_mov_b32_e32 v7, v1
	ds_read2_b32 v[8:9], v77 offset0:16 offset1:24
	ds_read2_b32 v[10:11], v77 offset0:81 offset1:89
	ds_read2_b32 v[12:13], v77 offset0:146 offset1:154
	ds_read2_b32 v[14:15], v77 offset0:211 offset1:219
	ds_read2_b32 v[16:17], v90 offset0:20 offset1:28
	ds_read2_b32 v[18:19], v90 offset0:85 offset1:93
	ds_read2_b32 v[20:21], v90 offset0:150 offset1:158
	ds_read2_b32 v[24:25], v90 offset0:215 offset1:223
	v_lshl_add_u64 v[6:7], v[22:23], 0, v[6:7]
	global_store_dwordx4 v[6:7], v[2:5], off
	v_or_b32_e32 v6, s12, v79
	v_mul_u32_u24_e32 v6, 0xb00, v6
	v_lshlrev_b32_e32 v6, 1, v6
	v_mov_b32_e32 v7, v1
	s_waitcnt lgkmcnt(6)
	v_cvt_pk_bf16_f32 v2, v8, v10
	s_waitcnt lgkmcnt(4)
	v_cvt_pk_bf16_f32 v3, v12, v14
	s_waitcnt lgkmcnt(2)
	v_cvt_pk_bf16_f32 v4, v16, v18
	s_waitcnt lgkmcnt(0)
	v_cvt_pk_bf16_f32 v5, v20, v24
	v_lshl_add_u64 v[6:7], v[22:23], 0, v[6:7]
	global_store_dwordx4 v[6:7], v[2:5], off
	v_or_b32_e32 v6, s12, v80
	v_mul_u32_u24_e32 v6, 0xb00, v6
	v_cvt_pk_bf16_f32 v2, v9, v11
	v_cvt_pk_bf16_f32 v3, v13, v15
	v_cvt_pk_bf16_f32 v4, v17, v19
	v_cvt_pk_bf16_f32 v5, v21, v25
	v_lshlrev_b32_e32 v6, 1, v6
	v_mov_b32_e32 v7, v1
	ds_read2_b32 v[8:9], v77 offset0:32 offset1:40
	ds_read2_b32 v[10:11], v77 offset0:97 offset1:105
	ds_read2_b32 v[12:13], v77 offset0:162 offset1:170
	ds_read2_b32 v[14:15], v77 offset0:227 offset1:235
	ds_read2_b32 v[16:17], v90 offset0:36 offset1:44
	ds_read2_b32 v[18:19], v90 offset0:101 offset1:109
	ds_read2_b32 v[20:21], v90 offset0:166 offset1:174
	ds_read2_b32 v[24:25], v90 offset0:231 offset1:239
	v_lshl_add_u64 v[6:7], v[22:23], 0, v[6:7]
	global_store_dwordx4 v[6:7], v[2:5], off
	v_or_b32_e32 v6, s12, v81
	v_mul_u32_u24_e32 v6, 0xb00, v6
	v_lshlrev_b32_e32 v6, 1, v6
	v_mov_b32_e32 v7, v1
	s_waitcnt lgkmcnt(6)
	v_cvt_pk_bf16_f32 v2, v8, v10
	s_waitcnt lgkmcnt(4)
	v_cvt_pk_bf16_f32 v3, v12, v14
	s_waitcnt lgkmcnt(2)
	v_cvt_pk_bf16_f32 v4, v16, v18
	s_waitcnt lgkmcnt(0)
	v_cvt_pk_bf16_f32 v5, v20, v24
	v_lshl_add_u64 v[6:7], v[22:23], 0, v[6:7]
	global_store_dwordx4 v[6:7], v[2:5], off
	v_or_b32_e32 v6, s12, v82
	v_mul_u32_u24_e32 v6, 0xb00, v6
	v_cvt_pk_bf16_f32 v2, v9, v11
	v_cvt_pk_bf16_f32 v3, v13, v15
	v_cvt_pk_bf16_f32 v4, v17, v19
	v_cvt_pk_bf16_f32 v5, v21, v25
	v_lshlrev_b32_e32 v6, 1, v6
	v_mov_b32_e32 v7, v1
	ds_read2_b32 v[8:9], v77 offset0:48 offset1:56
	ds_read2_b32 v[10:11], v77 offset0:113 offset1:121
	ds_read2_b32 v[12:13], v77 offset0:178 offset1:186
	ds_read2_b32 v[14:15], v77 offset0:243 offset1:251
	ds_read2_b32 v[16:17], v90 offset0:52 offset1:60
	ds_read2_b32 v[18:19], v90 offset0:117 offset1:125
	ds_read2_b32 v[20:21], v90 offset0:182 offset1:190
	ds_read2_b32 v[24:25], v90 offset0:247 offset1:255
	v_lshl_add_u64 v[6:7], v[22:23], 0, v[6:7]
	global_store_dwordx4 v[6:7], v[2:5], off
	v_or_b32_e32 v6, s12, v83
	v_mul_u32_u24_e32 v6, 0xb00, v6
	v_lshlrev_b32_e32 v6, 1, v6
	v_mov_b32_e32 v7, v1
	s_waitcnt lgkmcnt(6)
	v_cvt_pk_bf16_f32 v2, v8, v10
	s_waitcnt lgkmcnt(4)
	v_cvt_pk_bf16_f32 v3, v12, v14
	s_waitcnt lgkmcnt(2)
	v_cvt_pk_bf16_f32 v4, v16, v18
	s_waitcnt lgkmcnt(0)
	v_cvt_pk_bf16_f32 v5, v20, v24
	v_lshl_add_u64 v[6:7], v[22:23], 0, v[6:7]
	global_store_dwordx4 v[6:7], v[2:5], off
	v_or_b32_e32 v6, s12, v84
	v_mul_u32_u24_e32 v6, 0xb00, v6
	v_lshlrev_b32_e32 v6, 1, v6
	v_mov_b32_e32 v7, v1
	v_cvt_pk_bf16_f32 v2, v9, v11
	v_cvt_pk_bf16_f32 v3, v13, v15
	v_cvt_pk_bf16_f32 v4, v17, v19
	v_cvt_pk_bf16_f32 v5, v21, v25
	v_lshl_add_u64 v[6:7], v[22:23], 0, v[6:7]
	global_store_dwordx4 v[6:7], v[2:5], off
	s_waitcnt lgkmcnt(0)
.LBB0_952:
	s_andn2_b64 vcc, exec, s[10:11]
	s_cbranch_vccnz .LBB0_949
	s_mul_hi_i32 s0, s8, 0x2e8ba2e9
	s_lshr_b32 s10, s0, 31
	s_ashr_i32 s0, s0, 4
	s_add_i32 s10, s0, s10
	s_mul_i32 s0, s10, 0xffffffa8
	s_add_i32 s11, s8, s0
	s_mul_i32 s0, s11, 47
	s_sext_i32_i16 s12, s0
	s_ashr_i32 s12, s12, 11
	s_bfe_u32 s0, s0, 0x1000f
	s_add_i32 s0, s12, s0
	s_mul_i32 s12, s0, 44
	s_sub_i32 s12, s11, s12
	s_sext_i32_i8 s16, s12
	s_lshl_b32 s12, s16, 6
	s_add_i32 s11, s11, 43
	s_cmpk_lt_u32 s11, 0x57
	s_cselect_b32 s13, s74, s76
	s_cselect_b32 s11, s75, s77
	s_add_u32 s17, s13, s7
	s_addc_u32 s11, s11, 0
	s_ashr_i32 s13, s12, 31
	s_lshl_b32 s10, s10, 6
	s_lshl_b64 s[14:15], s[12:13], 2
	s_add_u32 s14, s17, s14
	v_or_b32_e32 v74, s10, v66
	s_addc_u32 s15, s11, s15
	v_lshl_add_u64 v[2:3], s[14:15], 0, v[0:1]
	v_or_b32_e32 v6, 4, v74
	v_mad_i64_i32 v[4:5], s[14:15], v74, s67, v[2:3]
	v_mad_i64_i32 v[6:7], s[14:15], v6, s67, v[2:3]
	global_load_dwordx4 v[62:65], v[4:5], off nt
	global_load_dwordx4 v[58:61], v[6:7], off nt
	v_or_b32_e32 v4, 8, v74
	v_or_b32_e32 v6, 12, v74
	v_mad_i64_i32 v[4:5], s[14:15], v4, s67, v[2:3]
	v_mad_i64_i32 v[6:7], s[14:15], v6, s67, v[2:3]
	global_load_dwordx4 v[54:57], v[4:5], off nt
	global_load_dwordx4 v[50:53], v[6:7], off nt
	v_or_b32_e32 v4, 16, v74
	v_or_b32_e32 v6, 20, v74
	v_mad_i64_i32 v[4:5], s[14:15], v4, s67, v[2:3]
	v_mad_i64_i32 v[6:7], s[14:15], v6, s67, v[2:3]
	global_load_dwordx4 v[46:49], v[4:5], off nt
	global_load_dwordx4 v[42:45], v[6:7], off nt
	v_or_b32_e32 v4, 24, v74
	v_or_b32_e32 v6, 28, v74
	v_mad_i64_i32 v[4:5], s[14:15], v4, s67, v[2:3]
	v_mad_i64_i32 v[6:7], s[14:15], v6, s67, v[2:3]
	global_load_dwordx4 v[38:41], v[4:5], off nt
	global_load_dwordx4 v[34:37], v[6:7], off nt
	v_or_b32_e32 v4, 32, v74
	v_or_b32_e32 v6, 36, v74
	v_mad_i64_i32 v[4:5], s[14:15], v4, s67, v[2:3]
	v_mad_i64_i32 v[6:7], s[14:15], v6, s67, v[2:3]
	global_load_dwordx4 v[30:33], v[4:5], off nt
	global_load_dwordx4 v[26:29], v[6:7], off nt
	v_or_b32_e32 v4, 40, v74
	v_or_b32_e32 v6, 44, v74
	v_mad_i64_i32 v[4:5], s[14:15], v4, s67, v[2:3]
	v_mad_i64_i32 v[6:7], s[14:15], v6, s67, v[2:3]
	global_load_dwordx4 v[22:25], v[4:5], off nt
	global_load_dwordx4 v[18:21], v[6:7], off nt
	v_or_b32_e32 v4, 48, v74
	v_or_b32_e32 v6, 52, v74
	v_mad_i64_i32 v[4:5], s[14:15], v4, s67, v[2:3]
	v_mad_i64_i32 v[6:7], s[14:15], v6, s67, v[2:3]
	global_load_dwordx4 v[14:17], v[4:5], off nt
	global_load_dwordx4 v[10:13], v[6:7], off nt
	v_or_b32_e32 v4, 56, v74
	v_or_b32_e32 v6, 60, v74
	v_mad_i64_i32 v[4:5], s[14:15], v4, s67, v[2:3]
	v_mad_i64_i32 v[2:3], s[14:15], v6, s67, v[2:3]
	global_load_dwordx4 v[6:9], v[4:5], off nt
	s_nop 0
	global_load_dwordx4 v[2:5], v[2:3], off nt
	v_cndmask_b32_e64 v75, 0, 1, s[24:25]
	v_cmp_ne_u32_e64 s[34:35], 1, v75
	s_andn2_b64 vcc, exec, s[24:25]
	s_cbranch_vccnz .LBB0_976
	v_ashrrev_i32_e32 v75, 31, v74
	v_lshl_add_u64 v[74:75], v[74:75], 2, s[2:3]
	global_load_dword v122, v[74:75], off
	global_load_dword v123, v[74:75], off offset:16
	global_load_dword v124, v[74:75], off offset:32
	global_load_dword v125, v[74:75], off offset:48
	global_load_dword v126, v[74:75], off offset:64
	global_load_dword v127, v[74:75], off offset:80
	global_load_dword v128, v[74:75], off offset:96
	global_load_dword v129, v[74:75], off offset:112
	global_load_dword v130, v[74:75], off offset:128
	global_load_dword v131, v[74:75], off offset:144
	global_load_dword v132, v[74:75], off offset:160
	global_load_dword v133, v[74:75], off offset:176
	global_load_dword v134, v[74:75], off offset:192
	global_load_dword v135, v[74:75], off offset:208
	global_load_dword v136, v[74:75], off offset:224
	global_load_dword v137, v[74:75], off offset:240
	s_ashr_i32 s11, s10, 31
	s_waitcnt vmcnt(0)
	v_mov_b32_e32 v74, v122
	v_pk_mul_f32 v[92:93], v[62:63], v[74:75] op_sel_hi:[1,0]
	v_pk_mul_f32 v[74:75], v[64:65], v[74:75] op_sel_hi:[1,0]
	ds_write2_b32 v87, v74, v75 offset0:2 offset1:3
	v_lshl_add_u64 v[74:75], s[10:11], 0, v[66:67]
	v_lshl_add_u64 v[74:75], v[74:75], 2, s[2:3]
	v_mov_b32_e32 v74, v123
	ds_write2_b32 v87, v92, v93 offset1:1
	s_cbranch_execnz .LBB0_956
